# phase1 conv-table loop: next Wup row prefetched one iteration ahead, convb load hoisted
# baseline (speedup 1.0000x reference)
.LBB0_578:
	s_or_b64 exec, exec, s[0:1]
	v_ashrrev_i32_e32 v1, 6, v2
	v_add_u32_e32 v66, s95, v1
	s_movk_i32 s0, 0x1600
	v_cmp_gt_i32_e32 vcc, s0, v66
	s_waitcnt lgkmcnt(0)
	s_barrier
	s_and_saveexec_b64 s[0:1], vcc
	s_cbranch_execz .LBB0_599
	v_mbcnt_lo_u32_b32 v1, -1, 0
	v_mbcnt_hi_u32_b32 v3, -1, v1
	v_and_b32_e32 v1, 64, v3
	v_add_u32_e32 v4, 64, v1
	v_xor_b32_e32 v1, 1, v3
	v_cmp_lt_i32_e32 vcc, v1, v4
	v_xor_b32_e32 v5, 2, v3
	v_and_b32_e32 v72, 63, v2
	v_cndmask_b32_e32 v1, v3, v1, vcc
	v_cmp_lt_i32_e32 vcc, v5, v4
	v_and_b32_e32 v80, 3, v2
	v_and_b32_e32 v2, 60, v2
	v_cndmask_b32_e32 v5, v3, v5, vcc
	v_lshlrev_b32_e32 v74, 2, v5
	v_xor_b32_e32 v5, 4, v3
	v_cmp_lt_i32_e32 vcc, v5, v4
	v_lshl_add_u32 v62, v72, 5, 0
	v_cmp_ne_u32_e64 s[12:13], 4, v2
	v_cndmask_b32_e32 v5, v3, v5, vcc
	v_lshlrev_b32_e32 v75, 2, v5
	v_xor_b32_e32 v5, 8, v3
	v_cmp_lt_i32_e32 vcc, v5, v4
	v_mul_u32_u24_e32 v68, 0x1600, v72
	s_waitcnt vmcnt(0)
	v_ashrrev_i32_e32 v67, 31, v66
	v_cndmask_b32_e32 v5, v3, v5, vcc
	v_lshlrev_b32_e32 v76, 2, v5
	v_xor_b32_e32 v5, 16, v3
	v_cmp_lt_i32_e32 vcc, v5, v4
	v_lshlrev_b32_e32 v68, 2, v68
	v_mov_b32_e32 v69, 0
	v_cndmask_b32_e32 v5, v3, v5, vcc
	v_lshlrev_b32_e32 v77, 2, v5
	v_xor_b32_e32 v5, 32, v3
	v_cmp_lt_i32_e32 vcc, v5, v4
	v_lshlrev_b64 v[70:71], 11, v[66:67]
	s_add_u32 s20, s86, 0x80000
	v_cndmask_b32_e32 v3, v3, v5, vcc
	v_lshlrev_b32_e32 v78, 2, v3
	v_subrev_co_u32_e32 v3, vcc, 12, v72
	v_cmp_eq_u32_e64 s[6:7], 0, v3
	v_cmp_eq_u32_e64 s[8:9], 1, v3
	v_mul_i32_i24_e32 v79, 0x1600, v3
	ds_read_b128 v[2:5], v62
	ds_read_b128 v[6:9], v62 offset:16
	ds_read_b128 v[10:13], v62 offset:4096
	ds_read_b128 v[14:17], v62 offset:4112
	ds_read_b128 v[18:21], v62 offset:8192
	ds_read_b128 v[22:25], v62 offset:8208
	ds_read_b128 v[26:29], v62 offset:12288
	ds_read_b128 v[30:33], v62 offset:12304
	ds_read_b128 v[34:37], v62 offset:2048
	ds_read_b128 v[38:41], v62 offset:2064
	ds_read_b128 v[42:45], v62 offset:6144
	ds_read_b128 v[46:49], v62 offset:6160
	ds_read_b128 v[50:53], v62 offset:10240
	ds_read_b128 v[54:57], v62 offset:10256
	ds_read_b128 v[58:61], v62 offset:14336
	ds_read_b128 v[62:65], v62 offset:14352
	v_lshl_add_u64 v[68:69], v[66:67], 2, v[68:69]
	v_lshl_or_b32 v70, v72, 4, v70
	s_addc_u32 s21, s87, 0
	v_lshl_add_u64 v[68:69], s[86:87], 0, v[68:69]
	s_mov_b64 s[28:29], 0x20000
	s_ashr_i32 s35, s34, 31
	v_lshl_add_u64 v[70:71], s[86:87], 0, v[70:71]
	s_mov_b64 s[30:31], 0x1600000
	v_lshlrev_b32_e32 v1, 2, v1
	s_xor_b64 s[26:27], vcc, -1
	v_cmp_gt_u32_e64 s[4:5], 15, v72
	v_cmp_lt_u32_e64 s[10:11], 3, v72
	v_cmp_eq_u32_e64 s[14:15], 2, v80
	v_lshl_add_u64 v[68:69], v[68:69], 0, s[28:29]
	s_lshl_b64 s[28:29], s[34:35], 2
	v_lshl_add_u64 v[70:71], v[70:71], 0, s[30:31]
	s_lshl_b64 s[30:31], s[34:35], 11
	s_mov_b64 s[36:37], 0
	s_movk_i32 s35, 0x7f
	s_movk_i32 s45, 0x15ff
	global_load_dwordx4 v[82:85], v[70:71], off
	global_load_dwordx4 v[86:89], v[70:71], off offset:1024
	s_waitcnt vmcnt(0)
	s_branch .LBB0_583

.LBB0_581:
	s_or_b64 exec, exec, s[40:41]
	s_waitcnt vmcnt(0)
	v_fma_f32 v72, v67, v73, v188
	global_store_dword v[68:69], v72, off
.LBB0_582:
	s_or_b64 exec, exec, s[38:39]
	s_waitcnt vmcnt(2) lgkmcnt(0)
	v_mov_b32_e32 v82, v172
	v_mov_b32_e32 v83, v173
	v_mov_b32_e32 v84, v174
	v_mov_b32_e32 v85, v175
	v_mov_b32_e32 v86, v176
	v_mov_b32_e32 v87, v177
	v_mov_b32_e32 v88, v178
	v_mov_b32_e32 v89, v179
	v_add_u32_e32 v66, s34, v66
	v_cmp_lt_i32_e32 vcc, s45, v66
	v_lshl_add_u64 v[68:69], v[68:69], 0, s[28:29]
	s_or_b64 s[36:37], vcc, s[36:37]
	v_lshl_add_u64 v[70:71], v[70:71], 0, s[30:31]
	s_andn2_b64 exec, exec, s[36:37]
	s_cbranch_execz .LBB0_599
.LBB0_583:
	v_lshl_add_u64 v[180:181], v[70:71], 0, s[30:31]
	global_load_dwordx4 v[172:175], v[180:181], off
	global_load_dwordx4 v[176:179], v[180:181], off offset:1024
	v_bfe_i32 v67, v66, 7, 1
	v_ashrrev_i32_e32 v72, 1, v66
	v_and_b32_e32 v67, 0xb00, v67
	v_and_b32_e32 v72, 0xffffff80, v72
	v_add_u32_e32 v67, v67, v72
	v_and_or_b32 v72, v66, s35, v67
	v_and_b32_e32 v73, 0xffff0000, v82
	v_lshlrev_b32_e32 v67, 16, v82
	v_lshlrev_b32_e32 v81, 16, v83
	v_and_b32_e32 v82, 0xffff0000, v83
	v_lshlrev_b32_e32 v83, 16, v84
	v_and_b32_e32 v84, 0xffff0000, v84
	v_lshlrev_b32_e32 v92, 16, v87
	v_and_b32_e32 v93, 0xffff0000, v87
	s_waitcnt lgkmcnt(14)
	v_mul_f32_e32 v87, v3, v73
	s_waitcnt lgkmcnt(13)
	v_mul_f32_e32 v94, v11, v73
	s_waitcnt lgkmcnt(11)
	v_mul_f32_e32 v95, v19, v73
	s_waitcnt lgkmcnt(9)
	v_mul_f32_e32 v73, v27, v73
	v_mul_f32_e32 v96, v5, v82
	v_mul_f32_e32 v97, v13, v82
	v_mul_f32_e32 v98, v21, v82
	v_mul_f32_e32 v82, v29, v82
	v_mul_f32_e32 v99, v7, v84
	v_mul_f32_e32 v100, v15, v84
	v_mul_f32_e32 v101, v23, v84
	s_waitcnt lgkmcnt(8)
	v_mul_f32_e32 v84, v31, v84
	v_fmac_f32_e32 v95, v18, v67
	v_fmac_f32_e32 v73, v26, v67
	s_waitcnt lgkmcnt(0)
	v_lshlrev_b32_e32 v90, 16, v85
	v_and_b32_e32 v85, 0xffff0000, v85
	v_fmac_f32_e32 v98, v20, v81
	v_fmac_f32_e32 v82, v28, v81
	v_fmac_f32_e32 v99, v6, v83
	v_fmac_f32_e32 v100, v14, v83
	v_fmac_f32_e32 v101, v22, v83
	v_fmac_f32_e32 v84, v30, v83
	v_add_f32_e32 v83, 0, v95
	v_add_f32_e32 v73, 0, v73
	v_lshlrev_b32_e32 v91, 16, v86
	v_and_b32_e32 v86, 0xffff0000, v86
	v_mul_f32_e32 v102, v9, v85
	v_mul_f32_e32 v103, v17, v85
	v_mul_f32_e32 v104, v25, v85
	v_mul_f32_e32 v85, v33, v85
	v_add_f32_e32 v83, v83, v98
	v_add_f32_e32 v73, v73, v82
	s_waitcnt lgkmcnt(7)
	v_mul_f32_e32 v105, v35, v86
	s_waitcnt lgkmcnt(5)
	v_mul_f32_e32 v106, v43, v86
	s_waitcnt lgkmcnt(3)
	v_mul_f32_e32 v107, v51, v86
	s_waitcnt lgkmcnt(1)
	v_mul_f32_e32 v86, v59, v86
	v_fmac_f32_e32 v104, v24, v90
	v_fmac_f32_e32 v85, v32, v90
	v_add_f32_e32 v82, v83, v101
	v_add_f32_e32 v73, v73, v84
	v_mul_f32_e32 v110, v53, v93
	v_fmac_f32_e32 v87, v2, v67
	v_fmac_f32_e32 v94, v10, v67
	v_fmac_f32_e32 v107, v50, v91
	v_fmac_f32_e32 v86, v58, v91
	v_add_f32_e32 v82, v82, v104
	v_add_f32_e32 v73, v73, v85
	v_fmac_f32_e32 v96, v4, v81
	v_fmac_f32_e32 v97, v12, v81
	v_fmac_f32_e32 v102, v8, v90
	v_fmac_f32_e32 v103, v16, v90
	v_fmac_f32_e32 v110, v52, v92
	v_add_f32_e32 v67, 0, v87
	v_add_f32_e32 v81, 0, v94
	v_add_f32_e32 v82, v82, v107
	v_add_f32_e32 v90, v73, v86
	v_ashrrev_i32_e32 v73, 31, v72
	v_add_f32_e32 v67, v67, v96
	v_add_f32_e32 v81, v81, v97
	v_add_f32_e32 v95, v82, v110
	v_lshl_add_u64 v[82:83], v[72:73], 2, s[76:77]
	v_add_f32_e32 v67, v67, v99
	v_add_f32_e32 v81, v81, v100
	v_add_co_u32_e32 v84, vcc, 0x5000, v82
	v_mul_f32_e32 v108, v37, v93
	v_mul_f32_e32 v109, v45, v93
	v_fmac_f32_e32 v105, v34, v91
	v_fmac_f32_e32 v106, v42, v91
	v_add_f32_e32 v67, v67, v102
	v_add_f32_e32 v81, v81, v103
	v_addc_co_u32_e32 v85, vcc, 0, v83, vcc
	v_fmac_f32_e32 v108, v36, v92
	v_fmac_f32_e32 v109, v44, v92
	v_add_f32_e32 v67, v67, v105
	v_add_f32_e32 v81, v81, v106
	v_add_co_u32_e32 v86, vcc, 0xb000, v82
	v_add_f32_e32 v91, v67, v108
	v_add_f32_e32 v94, v81, v109
	v_addc_co_u32_e32 v87, vcc, 0, v83, vcc
	global_load_dword v82, v[82:83], off
	s_nop 0
	global_load_dword v81, v[84:85], off offset:2048
	global_load_dword v67, v[86:87], off
	v_lshl_add_u64 v[182:183], v[72:73], 2, s[78:79]
	global_load_dword v188, v[182:183], off
	v_and_b32_e32 v85, 0xffff0000, v88
	v_lshlrev_b32_e32 v84, 16, v88
	v_mul_f32_e32 v86, v39, v85
	v_and_b32_e32 v88, 0xffff0000, v89
	v_fmac_f32_e32 v86, v38, v84
	v_lshlrev_b32_e32 v87, 16, v89
	v_mul_f32_e32 v89, v41, v88
	v_add_f32_e32 v86, v91, v86
	v_fmac_f32_e32 v89, v40, v87
	v_add_f32_e32 v86, v86, v89
	ds_bpermute_b32 v89, v1, v86
	v_mul_f32_e32 v83, v61, v93
	v_fmac_f32_e32 v83, v60, v92
	v_add_f32_e32 v83, v90, v83
	v_mul_f32_e32 v90, v47, v85
	s_waitcnt lgkmcnt(0)
	v_add_f32_e32 v86, v86, v89
	ds_bpermute_b32 v89, v74, v86
	v_mul_f32_e32 v91, v55, v85
	v_mul_f32_e32 v85, v63, v85
	v_fmac_f32_e32 v85, v62, v84
	v_add_f32_e32 v83, v83, v85
	s_waitcnt lgkmcnt(0)
	v_add_f32_e32 v86, v86, v89
	ds_bpermute_b32 v89, v75, v86
	v_fmac_f32_e32 v90, v46, v84
	v_fmac_f32_e32 v91, v54, v84
	v_mul_f32_e32 v84, v49, v88
	v_add_f32_e32 v90, v94, v90
	s_waitcnt lgkmcnt(0)
	v_add_f32_e32 v85, v86, v89
	ds_bpermute_b32 v86, v76, v85
	v_fmac_f32_e32 v84, v48, v87
	v_add_f32_e32 v89, v90, v84
	v_mul_f32_e32 v84, v57, v88
	v_add_f32_e32 v91, v95, v91
	v_fmac_f32_e32 v84, v56, v87
	v_add_f32_e32 v90, v91, v84
	s_waitcnt lgkmcnt(0)
	v_add_f32_e32 v84, v85, v86
	ds_bpermute_b32 v85, v77, v84
	v_mul_f32_e32 v86, v65, v88
	v_fmac_f32_e32 v86, v64, v87
	v_add_f32_e32 v83, v83, v86
	ds_bpermute_b32 v87, v1, v89
	s_waitcnt lgkmcnt(1)
	v_add_f32_e32 v84, v84, v85
	ds_bpermute_b32 v85, v1, v90
	ds_bpermute_b32 v88, v1, v83
	ds_bpermute_b32 v86, v78, v84
	s_waitcnt lgkmcnt(3)
	v_add_f32_e32 v87, v89, v87
	ds_bpermute_b32 v89, v74, v87
	s_waitcnt lgkmcnt(3)
	v_add_f32_e32 v85, v90, v85
	s_waitcnt lgkmcnt(2)
	v_add_f32_e32 v83, v83, v88
	ds_bpermute_b32 v90, v74, v85
	ds_bpermute_b32 v88, v74, v83
	s_waitcnt lgkmcnt(2)
	v_add_f32_e32 v87, v87, v89
	ds_bpermute_b32 v89, v75, v87
	s_waitcnt lgkmcnt(2)
	v_add_f32_e32 v85, v85, v90
	s_waitcnt lgkmcnt(1)
	v_add_f32_e32 v83, v83, v88
	ds_bpermute_b32 v90, v75, v85
	ds_bpermute_b32 v88, v75, v83
	s_waitcnt lgkmcnt(2)
	v_add_f32_e32 v87, v87, v89
	ds_bpermute_b32 v89, v76, v87
	s_waitcnt lgkmcnt(2)
	v_add_f32_e32 v85, v85, v90
	s_waitcnt lgkmcnt(1)
	v_add_f32_e32 v83, v83, v88
	ds_bpermute_b32 v90, v76, v85
	ds_bpermute_b32 v88, v76, v83
	s_waitcnt lgkmcnt(2)
	v_add_f32_e32 v87, v87, v89
	ds_bpermute_b32 v89, v77, v87
	s_waitcnt lgkmcnt(2)
	v_add_f32_e32 v90, v85, v90
	s_waitcnt lgkmcnt(1)
	v_add_f32_e32 v92, v83, v88
	ds_bpermute_b32 v91, v77, v90
	ds_bpermute_b32 v93, v77, v92
	s_waitcnt lgkmcnt(2)
	v_add_f32_e32 v83, v87, v89
	ds_bpermute_b32 v85, v78, v83
	s_waitcnt lgkmcnt(2)
	v_add_f32_e32 v87, v90, v91
	s_waitcnt lgkmcnt(1)
	v_add_f32_e32 v89, v92, v93
	ds_bpermute_b32 v88, v78, v87
	ds_bpermute_b32 v90, v78, v89
	s_and_saveexec_b64 s[38:39], s[26:27]
	s_xor_b64 s[38:39], exec, s[38:39]
	s_cbranch_execz .LBB0_587
	s_and_saveexec_b64 s[40:41], s[4:5]
	s_cbranch_execz .LBB0_586
	v_add_u32_e32 v72, v79, v66
	v_ashrrev_i32_e32 v73, 31, v72
	s_waitcnt vmcnt(0)
	v_cndmask_b32_e64 v67, v67, v81, s[8:9]
	v_lshl_add_u64 v[72:73], v[72:73], 2, s[20:21]
	v_cndmask_b32_e64 v67, v67, v82, s[6:7]
	global_store_dword v[72:73], v67, off

.LBB0_587:
	s_andn2_saveexec_b64 s[38:39], s[38:39]
	s_cbranch_execz .LBB0_582
	s_and_saveexec_b64 s[40:41], s[10:11]
	s_cbranch_execz .LBB0_594
	s_and_saveexec_b64 s[50:51], s[12:13]
	s_xor_b64 s[50:51], exec, s[50:51]
	s_cbranch_execz .LBB0_591
	s_waitcnt vmcnt(2)
	v_add_f32_e32 v73, v82, v81
	s_waitcnt vmcnt(1)
	v_add_f32_e32 v67, v73, v67
